# final candidate: P3 q-GEMM rebalance (grid-size generic) + GEMM accumulate-chain MFMA order + P15 carry-prefix loads batched
# speedup vs baseline: 1.1006x; 1.1006x over previous
;     __host__ __device__ bool next(int i, Unit& u) const {
;         const long L = (long)i * G + c; if (L >= nwg) return false;
;         int wgid = (int)L; { const int q = nwg / NXCD, r = nwg % NXCD, xcd = wgid % NXCD, off = wgid / NXCD; wgid = (xcd < r ? xcd * (q + 1) : r * (q + 1) + (xcd - r) * q) + off; }
;         const int nig = WGM * nN, gid = wgid / nig, fm = gid * WGM, gsz = (nM - fm) < WGM ? (nM - fm) : WGM;
;         u.pm = fm + ((wgid % nig) % gsz); u.pn = (wgid % nig) / gsz; return true;
.LBB0_398:
	s_add_i32 s41, s41, 1
	s_sub_i32 s5, s76, 8
	s_mul_i32 s4, s41, s5
	s_add_u32 s4, s4, s100
	s_mov_b32 s5, 0
	v_cmp_gt_i64_e32 vcc, s[4:5], v[142:143]
	v_cmp_lt_i64_e64 s[6:7], s[4:5], v[140:141]
	s_cbranch_vccnz .LBB0_400
	s_ashr_i32 s5, s4, 31
	s_lshr_b32 s5, s5, 29
	s_add_i32 s5, s4, s5
	s_ashr_i32 s22, s5, 3
	s_and_b32 s5, s5, -8
	s_sub_i32 s4, s4, s5
	s_cmp_lt_i32 s4, 0
	s_cselect_b32 s5, s39, 0x48
	s_mul_i32 s4, s4, s5
	s_add_i32 s4, s4, s22
	s_mul_hi_i32 s5, s4, 0x38e38e39
	s_lshr_b32 s22, s5, 31
	s_ashr_i32 s5, s5, 3
	s_add_i32 s5, s5, s22
	s_lshl_b32 s22, s5, 2
	s_sub_i32 s23, 64, s22
	s_min_i32 s23, s23, 4
	s_abs_i32 s24, s23
	v_cvt_f32_u32_e32 v0, s24
	s_sub_i32 s26, 0, s24
	s_mul_i32 s5, s5, 36
	s_sub_i32 s4, s4, s5
	v_rcp_iflag_f32_e32 v0, v0
	s_abs_i32 s5, s4
	s_xor_b32 s25, s4, s23
	s_ashr_i32 s25, s25, 31
	v_mul_f32_e32 v0, 0x4f7ffffe, v0
	v_cvt_u32_f32_e32 v0, v0
	s_nop 0
	v_readfirstlane_b32 s27, v0
	s_mul_i32 s26, s26, s27
	s_mul_hi_u32 s26, s27, s26
	s_add_i32 s27, s27, s26
	s_mul_hi_u32 s26, s5, s27
	s_mul_i32 s27, s26, s24
	s_sub_i32 s5, s5, s27
	s_add_i32 s48, s26, 1
	s_sub_i32 s27, s5, s24
	s_cmp_ge_u32 s5, s24
	s_cselect_b32 s26, s48, s26
	s_cselect_b32 s5, s27, s5
	s_add_i32 s27, s26, 1
	s_cmp_ge_u32 s5, s24
	s_cselect_b32 s5, s27, s26
	s_xor_b32 s5, s5, s25
	s_sub_i32 s48, s5, s25
	s_mul_i32 s5, s48, s23
	s_sub_i32 s4, s4, s5
	s_add_i32 s22, s22, s4
